# RWKV producer: y write-out moved to the top of the chunk iteration so its store is not drained at the bottom
# speedup vs baseline: 1.0059x; 1.0014x over previous
.LBB0_731:
	s_cmp_gt_u32 s63, 1
	s_cselect_b64 s[40:41], -1, 0
	s_andn2_b64 vcc, exec, s[40:41]
	s_cbranch_vccnz .Lprod_ytop_skip
	s_and_b32 s0, s62, 0x200
	v_lshl_add_u32 v253, s0, 2, v144
	ds_read_b64 v[254:255], v253
	s_waitcnt lgkmcnt(0)
	v_cvt_pk_bf16_f32 v252, v254, v255
	v_lshl_add_u64 v[254:255], v[70:71], 0, s[16:17]
	v_lshlrev_b64 v[254:255], 11, v[254:255]
	v_lshl_add_u64 v[254:255], v[72:73], 0, v[254:255]
	global_store_dword v[254:255], v252, off
.Lprod_ytop_skip:
	s_and_b64 s[0:1], s[36:37], s[40:41]
	v_cmp_gt_i32_e32 vcc, s54, v29
	s_and_b64 s[42:43], s[0:1], vcc
	s_and_saveexec_b64 s[8:9], s[42:43]
	s_cbranch_execz .LBB0_765
	v_cmp_eq_u32_e32 vcc, 0, v67
	s_and_saveexec_b64 s[44:45], vcc
	s_cbranch_execz .LBB0_748
	v_readlane_b32 s72, v235, 39
	v_readlane_b32 s82, v235, 49
	v_readlane_b32 s83, v235, 50
	v_cmp_lt_i32_e32 vcc, s55, v29
	v_mov_b32_e32 v2, 64
	v_mov_b32_e32 v33, 0x800
	v_mov_b64_e32 v[60:61], 0
	v_mov_b64_e32 v[64:65], s[26:27]
	v_mov_b64_e32 v[62:63], s[82:83]
	v_mov_b32_e32 v59, 0x800
	v_mov_b32_e32 v0, v29
	v_readlane_b32 s73, v235, 40
	v_readlane_b32 s74, v235, 41
	v_readlane_b32 s75, v235, 42
	v_readlane_b32 s76, v235, 43
	v_readlane_b32 s77, v235, 44
	v_readlane_b32 s78, v235, 45
	v_readlane_b32 s79, v235, 46
	v_readlane_b32 s80, v235, 47
	v_readlane_b32 s81, v235, 48
	v_readlane_b32 s84, v235, 51
	v_readlane_b32 s85, v235, 52
	v_readlane_b32 s86, v235, 53
	v_readlane_b32 s87, v235, 54
	s_and_saveexec_b64 s[46:47], vcc
	s_cbranch_execz .LBB0_747
	v_readlane_b32 s72, v235, 39
	v_readlane_b32 s76, v235, 43
	v_readlane_b32 s77, v235, 44
	v_readlane_b32 s78, v235, 45
	v_readlane_b32 s79, v235, 46
	v_readlane_b32 s80, v235, 47
	v_readlane_b32 s81, v235, 48
	v_readlane_b32 s82, v235, 49
	v_readlane_b32 s83, v235, 50
	v_readlane_b32 s84, v235, 51
	v_readlane_b32 s85, v235, 52
	v_readlane_b32 s86, v235, 53
	v_readlane_b32 s87, v235, 54
	v_mov_b64_e32 v[60:61], s[84:85]
	v_readlane_b32 s76, v235, 55
	v_readlane_b32 s77, v235, 56
	v_cmp_lt_u32_e32 vcc, s56, v29
	v_readlane_b32 s73, v235, 40
	v_mov_b64_e32 v[62:63], s[76:77]
	v_readlane_b32 s74, v235, 41
	v_readlane_b32 s75, v235, 42
	v_readlane_b32 s78, v235, 57
	v_readlane_b32 s79, v235, 58
	v_readlane_b32 s80, v235, 59
	v_readlane_b32 s81, v235, 60
	v_readlane_b32 s82, v235, 61
	v_readlane_b32 s83, v235, 62
	v_readlane_b32 s84, v235, 63
	v_readlane_b32 s85, v234, 0
	v_readlane_b32 s86, v234, 1
	v_readlane_b32 s87, v234, 2
	v_readlane_b32 s88, v234, 3
	v_readlane_b32 s89, v234, 4
	v_readlane_b32 s90, v234, 5
	v_readlane_b32 s91, v234, 6
	s_and_saveexec_b64 s[0:1], vcc
	s_xor_b64 s[48:49], exec, s[0:1]
	s_cbranch_execz .LBB0_744
	v_readlane_b32 s76, v235, 55
	v_readlane_b32 s82, v235, 61
	v_readlane_b32 s83, v235, 62
	v_cmp_lt_u32_e32 vcc, s57, v29
	v_readlane_b32 s77, v235, 56
	v_mov_b64_e32 v[62:63], s[82:83]
	v_readlane_b32 s78, v235, 57
	v_readlane_b32 s79, v235, 58
	v_readlane_b32 s80, v235, 59
	v_readlane_b32 s81, v235, 60
	v_readlane_b32 s84, v235, 63
	v_readlane_b32 s85, v234, 0
	v_readlane_b32 s86, v234, 1
	v_readlane_b32 s87, v234, 2
	v_readlane_b32 s88, v234, 3
	v_readlane_b32 s89, v234, 4
	v_readlane_b32 s90, v234, 5
	v_readlane_b32 s91, v234, 6
	s_and_saveexec_b64 s[0:1], vcc
	s_xor_b64 s[0:1], exec, s[0:1]
	s_cbranch_execz .LBB0_741
	v_readlane_b32 s76, v235, 55
	v_readlane_b32 s77, v235, 56
	v_readlane_b32 s78, v235, 57
	v_readlane_b32 s79, v235, 58
	v_readlane_b32 s80, v235, 59
	v_readlane_b32 s81, v235, 60
	v_readlane_b32 s82, v235, 61
	v_readlane_b32 s83, v235, 62
	v_readlane_b32 s84, v235, 63
	v_readlane_b32 s85, v234, 0
	v_readlane_b32 s86, v234, 1
	v_readlane_b32 s87, v234, 2
	v_readlane_b32 s88, v234, 3
	v_readlane_b32 s89, v234, 4
	v_readlane_b32 s90, v234, 5
	v_readlane_b32 s91, v234, 6
	s_mov_b64 s[76:77], s[84:85]
	s_mov_b64 s[78:79], s[86:87]
	v_cmp_lt_u32_e32 vcc, s58, v29
	v_mov_b64_e32 v[60:61], s[76:77]
	v_mov_b64_e32 v[62:63], s[78:79]
	s_mov_b64 s[80:81], s[88:89]
	s_mov_b64 s[82:83], s[90:91]
	s_and_saveexec_b64 s[50:51], vcc
	s_xor_b64 s[50:51], exec, s[50:51]
	s_cbranch_execz .LBB0_738
	v_readlane_b32 s76, v235, 55
	v_readlane_b32 s88, v234, 3
	v_readlane_b32 s89, v234, 4
	v_add_u32_e32 v0, 0xffffc800, v29
	v_mov_b64_e32 v[60:61], 0
	v_readlane_b32 s77, v235, 56
	v_readlane_b32 s78, v235, 57
	v_readlane_b32 s79, v235, 58
	v_readlane_b32 s80, v235, 59
	v_readlane_b32 s81, v235, 60
	v_readlane_b32 s82, v235, 61
	v_readlane_b32 s83, v235, 62
	v_readlane_b32 s84, v235, 63
	v_readlane_b32 s85, v234, 0
	v_readlane_b32 s86, v234, 1
	v_readlane_b32 s87, v234, 2
	v_readlane_b32 s90, v234, 5
	v_readlane_b32 s91, v234, 6
	v_mov_b64_e32 v[62:63], s[88:89]

.LBB0_781:
	s_or_b64 exec, exec, s[8:9]
.LBB0_783:
	s_mov_b64 s[0:1], 0x800
	v_lshl_add_u64 v[78:79], v[78:79], 0, s[0:1]
	s_mov_b64 s[0:1], 0x10000
	s_add_i32 s63, s63, 1
	s_addk_i32 s62, 0x200
	s_add_i32 s16, s16, 32
	v_lshl_add_u64 v[80:81], v[80:81], 0, s[0:1]
	s_mov_b64 s[0:1], 0x60000
	s_cmp_eq_u32 s62, 0x10200
	v_lshl_add_u64 v[82:83], v[82:83], 0, s[0:1]
	s_waitcnt lgkmcnt(0)
	s_barrier
	s_cbranch_scc1 .LBB0_785
	s_waitcnt vmcnt(0)
	v_mov_b64_e32 v[84:85], v[200:201]
	v_mov_b64_e32 v[90:91], v[198:199]
	v_mov_b64_e32 v[92:93], v[196:197]
	v_mov_b64_e32 v[88:89], v[192:193]
	v_mov_b64_e32 v[94:95], v[194:195]
	v_mov_b64_e32 v[96:97], v[188:189]
	v_mov_b64_e32 v[98:99], v[190:191]
	v_mov_b64_e32 v[86:87], v[186:187]
	v_mov_b64_e32 v[120:121], v[130:131]
	v_mov_b64_e32 v[122:123], v[128:129]
	v_mov_b64_e32 v[106:107], v[126:127]
	v_mov_b64_e32 v[102:103], v[118:119]
	v_mov_b64_e32 v[108:109], v[124:125]
	v_mov_b64_e32 v[104:105], v[114:115]
	v_mov_b64_e32 v[110:111], v[116:117]
	v_mov_b64_e32 v[100:101], v[112:113]
	s_branch .LBB0_731
